# early acquire + wave 7 performs sb_arrive (parallel with wave 0's poll) + redundant phase-end drain/barrier removed
# baseline (speedup 1.0000x reference)
.LBB0_150:
.LBB0_151:
	s_mov_b64 s[4:5], 0

.LBB0_170:
.LBB0_171:
	s_waitcnt vmcnt(0)
	v_readlane_b32 s0, v255, 60
	v_readlane_b32 s1, v255, 61
	s_and_b64 vcc, exec, s[0:1]
	s_waitcnt vmcnt(0)
	s_barrier
	s_cbranch_vccnz .LBB0_113
	v_mbcnt_lo_u32_b32 v0, -1, 0
	v_mbcnt_hi_u32_b32 v0, -1, v0
	s_nop 0
	v_cmp_eq_u32_e32 vcc, 0, v0
	s_and_saveexec_b64 s[4:5], vcc
	s_cbranch_execz .LBB0_112
	s_mul_i32 s1, s63, 0x220
	v_readlane_b32 s2, v255, 12
	s_mul_hi_i32 s0, s63, 0x220
	s_add_u32 s8, s2, s1
	v_readlane_b32 s1, v255, 13
	s_addc_u32 s9, s1, s0
	s_mov_b32 s0, s86
	v_readlane_b32 s1, v255, 19
	s_lshl_b32 s56, s0, 3
	s_waitcnt vmcnt(0) expcnt(0) lgkmcnt(0)
	v_mov_b32_e32 v0, s1
	s_lshl_b64 s[0:1], s[56:57], 2
	s_add_u32 s0, s8, s0
	s_addc_u32 s1, s9, s1
	v_mov_b64_e32 v[2:3], s[0:1]
	ds_read_b32 v0, v0
	flat_atomic_add v2, v[2:3], v201 sc0
	s_waitcnt vmcnt(0) lgkmcnt(0)
	v_add_u32_e32 v2, 1, v2
	v_cmp_eq_u32_e32 vcc, v2, v0
	s_and_b64 exec, exec, vcc
	s_cbranch_execz .LBB0_112
	buffer_wbl2 sc1
	s_waitcnt vmcnt(0)
	v_mov_b64_e32 v[2:3], s[8:9]
	flat_atomic_add v[2:3], v201 offset:512
	s_branch .LBB0_112

.LBB0_232:
	s_setprio 0
	s_waitcnt vmcnt(0) lgkmcnt(0)
	s_barrier
	s_waitcnt vmcnt(0)
	v_readlane_b32 s0, v255, 60
	v_readlane_b32 s1, v255, 61
	v_readlane_b32 s88, v255, 22
	v_readlane_b32 s92, v255, 24
	s_and_b64 vcc, exec, s[0:1]
	v_readlane_b32 s89, v255, 23
	v_readlane_b32 s93, v255, 25
	v_readlane_b32 s94, v255, 26
	v_readlane_b32 s95, v255, 27
	s_waitcnt vmcnt(0) lgkmcnt(0)
	s_barrier
	s_cbranch_vccnz .LBB0_179
	v_mbcnt_lo_u32_b32 v0, -1, 0
	v_mbcnt_hi_u32_b32 v0, -1, v0
	s_nop 0
	v_cmp_eq_u32_e32 vcc, 0, v0
	s_and_saveexec_b64 s[4:5], vcc
	s_cbranch_execz .LBB0_178
	s_mul_i32 s1, s62, 0x220
	v_readlane_b32 s2, v255, 12
	s_mul_hi_i32 s0, s62, 0x220
	s_add_u32 s6, s2, s1
	v_readlane_b32 s1, v255, 13
	s_addc_u32 s7, s1, s0
	s_mov_b32 s0, s86
	v_readlane_b32 s1, v255, 19
	s_lshl_b32 s56, s0, 3
	s_waitcnt vmcnt(0) expcnt(0) lgkmcnt(0)
	v_mov_b32_e32 v0, s1
	s_lshl_b64 s[0:1], s[56:57], 2
	s_add_u32 s0, s6, s0
	s_addc_u32 s1, s7, s1
	v_mov_b64_e32 v[2:3], s[0:1]
	ds_read_b32 v0, v0
	flat_atomic_add v2, v[2:3], v201 sc0
	s_waitcnt vmcnt(0) lgkmcnt(0)
	v_add_u32_e32 v2, 1, v2
	v_cmp_eq_u32_e32 vcc, v2, v0
	s_and_b64 exec, exec, vcc
	s_cbranch_execz .LBB0_178
	buffer_wbl2 sc1
	s_waitcnt vmcnt(0)
	v_mov_b64_e32 v[2:3], s[6:7]
	flat_atomic_add v[2:3], v201 offset:512
	s_branch .LBB0_178

.LBB0_283:
	s_setprio 0
	s_waitcnt vmcnt(0) lgkmcnt(0)
	s_barrier
	s_waitcnt vmcnt(0)
	v_readlane_b32 s0, v255, 60
	v_readlane_b32 s1, v255, 61
	s_and_b64 vcc, exec, s[0:1]
	s_waitcnt vmcnt(0) lgkmcnt(0)
	s_barrier
	s_cbranch_vccnz .LBB0_240
	v_mbcnt_lo_u32_b32 v0, -1, 0
	v_mbcnt_hi_u32_b32 v0, -1, v0
	s_nop 0
	v_cmp_eq_u32_e32 vcc, 0, v0
	s_and_saveexec_b64 s[4:5], vcc
	s_cbranch_execz .LBB0_239
	s_mul_i32 s1, s63, 0x220
	v_readlane_b32 s2, v255, 12
	s_mul_hi_i32 s0, s63, 0x220
	s_add_u32 s6, s2, s1
	v_readlane_b32 s1, v255, 13
	s_addc_u32 s7, s1, s0
	s_mov_b32 s0, s86
	v_readlane_b32 s1, v255, 19
	s_lshl_b32 s56, s0, 3
	s_waitcnt vmcnt(0) expcnt(0) lgkmcnt(0)
	v_mov_b32_e32 v0, s1
	s_lshl_b64 s[0:1], s[56:57], 2
	s_add_u32 s0, s6, s0
	s_addc_u32 s1, s7, s1
	v_mov_b64_e32 v[2:3], s[0:1]
	ds_read_b32 v0, v0
	flat_atomic_add v2, v[2:3], v201 sc0
	s_waitcnt vmcnt(0) lgkmcnt(0)
	v_add_u32_e32 v2, 1, v2
	v_cmp_eq_u32_e32 vcc, v2, v0
	s_and_b64 exec, exec, vcc
	s_cbranch_execz .LBB0_239
	buffer_wbl2 sc1
	s_waitcnt vmcnt(0)
	v_mov_b64_e32 v[2:3], s[6:7]
	flat_atomic_add v[2:3], v201 offset:512
	s_branch .LBB0_239

.LBB0_406:
.LBB0_407:
	s_waitcnt vmcnt(0)
	v_readlane_b32 s4, v255, 60
	v_readlane_b32 s5, v255, 61
	s_and_b64 vcc, exec, s[4:5]
	s_waitcnt lgkmcnt(0)
	s_barrier
	s_cbranch_vccnz .LBB0_339
	v_mbcnt_lo_u32_b32 v0, -1, 0
	v_mbcnt_hi_u32_b32 v0, -1, v0
	s_nop 0
	v_cmp_eq_u32_e32 vcc, 0, v0
	s_and_saveexec_b64 s[4:5], vcc
	s_cbranch_execz .LBB0_338
	s_mul_i32 s6, s26, 0x220
	v_readlane_b32 s7, v255, 12
	s_mul_hi_i32 s3, s26, 0x220
	s_add_u32 s6, s7, s6
	v_readlane_b32 s7, v255, 13
	s_addc_u32 s7, s7, s3
	s_mov_b32 s3, s86
	v_readlane_b32 s8, v255, 19
	s_lshl_b32 s56, s3, 3
	s_waitcnt vmcnt(0) expcnt(0) lgkmcnt(0)
	v_mov_b32_e32 v0, s8
	s_lshl_b64 s[8:9], s[56:57], 2
	s_add_u32 s8, s6, s8
	s_addc_u32 s9, s7, s9
	v_mov_b64_e32 v[2:3], s[8:9]
	ds_read_b32 v0, v0
	flat_atomic_add v2, v[2:3], v201 sc0
	s_waitcnt vmcnt(0) lgkmcnt(0)
	v_add_u32_e32 v2, 1, v2
	v_cmp_eq_u32_e32 vcc, v2, v0
	s_and_b64 exec, exec, vcc
	s_cbranch_execz .LBB0_338
	buffer_wbl2 sc1
	s_waitcnt vmcnt(0)
	v_mov_b64_e32 v[2:3], s[6:7]
	flat_atomic_add v[2:3], v201 offset:512
	s_branch .LBB0_338
